# norm0: narrow GEMM hand-written (all 32 operand loads in flight, x prefetch behind them, LDS reduce as in the layer-0 post phase)
# speedup vs baseline: 1.0061x; 1.0035x over previous
; DI int otid() { int t = threadIdx.x; asm volatile("" : "+v"(t)); return t; }
; DI int osgpr(int v) { asm volatile("" : "+s"(v)); return v; }
; DI void skinny_tile(const P& p, int l, int r0, float* red) {
;     ...
;     const int tid = otid(), w = tid >> 6, lane = tid & 63, l15 = lane & 15, g = lane >> 4;
;     f32x4 acc[3];
; #pragma unroll
;     for (int n = 0; n < 3; ++n) acc[n] = (f32x4){0.f, 0.f, 0.f, 0.f};
;     const bf16_t* ap = A + (size_t)(r0 + l15) * DM + 256 * w + 8 * g;
;     const bf16_t* bp = Bt + (size_t)l15 * DM + 256 * w + 8 * g;
; DI void norm0_phase(const P& p, unsigned char* smem) {
;     const int tid = otid(); const int wave = tid >> 6, lane = tid & 63;
;     const float* mod = (const float*)(p.ws + WS_MOD);
;     bf16_t* nb = (bf16_t*)(p.ws + WS_NBUF);
;     for (int rt = osgpr(blockIdx.x); rt < NROW / 16; rt += gridDim.x) {
;       for (int rr = 0; rr < 2; ++rr) {
;         const int row = rt * 16 + wave * 2 + rr;
;         const float* h = row < NLAT ? p.x + (size_t)row * DM : p.ctx + (size_t)(row - NLAT) * DM;
;         const int mr = row < NLAT ? (row >> 11) : 4;
;         f32x4 v[8]; float ss = 0.f;
; #pragma unroll
;         for (int i = 0; i < 8; ++i) { v[i] = __builtin_nontemporal_load((const f32x4*)(h + i * 256 + lane * 4)); ss += v[i][0] * v[i][0] + v[i][1] * v[i][1] + v[i][2] * v[i][2] + v[i][3] * v[i][3]; }
.LBB0_94:
	s_or_b64 exec, exec, s[6:7]
	s_waitcnt lgkmcnt(0)
	s_barrier
	s_load_dwordx2 s[92:93], s[0:1], 0x0
	s_load_dwordx2 s[90:91], s[0:1], 0x10
	s_load_dwordx2 s[6:7], s[0:1], 0x30
	v_readlane_b32 s28, v253, 0
	s_mov_b64 s[8:9], 0
	s_mov_b32 s10, 0
	s_mov_b32 s11, s28
	v_mov_b32_e32 v0, v166
	s_cmpk_gt_i32 s28, 0x23f
	v_mbcnt_lo_u32_b32 v167, -1, 0
	s_cbranch_scc1 .LBB0_115
	v_ashrrev_i32_e32 v1, 5, v0
	v_and_b32_e32 v69, -2, v1
	v_mbcnt_hi_u32_b32 v1, -1, v167
	v_and_b32_e32 v2, 64, v1
	v_add_u32_e32 v2, 64, v2
	v_xor_b32_e32 v3, 32, v1
	v_cmp_lt_i32_e32 vcc, v3, v2
	s_add_u32 s14, s68, s8
	s_addc_u32 s15, s69, s9
	v_cndmask_b32_e32 v3, v1, v3, vcc
	v_lshlrev_b32_e32 v72, 2, v3
	v_xor_b32_e32 v3, 16, v1
	v_cmp_lt_i32_e32 vcc, v3, v2
	s_add_i32 s29, s10, 0
	v_lshlrev_b32_e32 v0, 2, v0
	v_cndmask_b32_e32 v3, v1, v3, vcc
	v_lshlrev_b32_e32 v73, 2, v3
	v_xor_b32_e32 v3, 8, v1
	v_cmp_lt_i32_e32 vcc, v3, v2
	s_add_u32 s8, s14, 0x4800000
	v_and_b32_e32 v0, 0xfc, v0
	v_cndmask_b32_e32 v3, v1, v3, vcc
	v_lshlrev_b32_e32 v74, 2, v3
	v_xor_b32_e32 v3, 4, v1
	v_cmp_lt_i32_e32 vcc, v3, v2
	s_addc_u32 s9, s15, 0
	v_mov_b32_e32 v33, 0
	v_cndmask_b32_e32 v3, v1, v3, vcc
	v_lshlrev_b32_e32 v75, 2, v3
	v_xor_b32_e32 v3, 2, v1
	v_or_b32_e32 v8, 0x400, v0
	v_lshlrev_b32_e32 v32, 2, v0
	s_add_u32 s10, s14, 0x483c000
	v_cmp_lt_i32_e32 vcc, v3, v2
	v_or_b32_e32 v10, 0x500, v0
	s_waitcnt lgkmcnt(0)
	v_lshl_add_u64 v[34:35], s[6:7], 0, v[32:33]
	v_lshlrev_b32_e32 v32, 2, v8
	s_addc_u32 s11, s15, 0
	v_cndmask_b32_e32 v3, v1, v3, vcc
	v_or_b32_e32 v12, 0x600, v0
	v_lshl_add_u64 v[36:37], s[6:7], 0, v[32:33]
	v_lshlrev_b32_e32 v32, 2, v10
	v_lshlrev_b32_e32 v76, 2, v3
	v_xor_b32_e32 v3, 1, v1
	v_or_b32_e32 v14, 0x700, v0
	v_lshl_add_u64 v[38:39], s[6:7], 0, v[32:33]
	v_lshlrev_b32_e32 v32, 2, v12
	s_add_u32 s12, s14, 0x17e4d200
	v_cmp_lt_i32_e32 vcc, v3, v2
	v_lshl_add_u64 v[40:41], s[6:7], 0, v[32:33]
	v_lshlrev_b32_e32 v32, 2, v14
	s_addc_u32 s13, s15, 0
	v_cndmask_b32_e32 v1, v1, v3, vcc
	v_or_b32_e32 v2, 0x100, v0
	v_or_b32_e32 v4, 0x200, v0
	v_or_b32_e32 v6, 0x300, v0
	v_lshl_add_u64 v[42:43], s[6:7], 0, v[32:33]
	s_add_u32 s31, s14, 0x17ead200
	v_lshlrev_b32_e32 v32, 1, v0
	v_lshlrev_b32_e32 v77, 2, v1
	s_movk_i32 s30, 0x300
	s_addc_u32 s34, s15, 0
	v_lshl_add_u64 v[44:45], s[10:11], 0, v[32:33]
	s_lshl_b32 s35, s28, 4
	s_lshl_b32 s36, s70, 4
	s_movk_i32 s37, 0x1fff
	v_lshlrev_b32_e32 v32, 2, v0
	s_movk_i32 s38, 0x1000
	v_mov_b32_e32 v78, 0x358637bd
	s_mov_b32 s39, 0x800000
	s_mov_b64 s[14:15], 0x2000
	v_lshlrev_b32_e32 v46, 2, v2
	v_lshlrev_b32_e32 v48, 2, v4
	v_lshlrev_b32_e32 v50, 2, v6
	v_lshlrev_b32_e32 v52, 2, v8
	v_lshlrev_b32_e32 v54, 2, v10
	v_lshlrev_b32_e32 v56, 2, v12
	v_lshlrev_b32_e32 v58, 2, v14
	s_mov_b32 s40, 0x10000
	s_mov_b32 s41, 0x20000
	s_movk_i32 s42, 0x1ff
	s_mov_b64 s[16:17], 0x800
	s_movk_i32 s43, 0xff
	v_and_b32_e32 v0, 63, v166
	v_lshrrev_b32_e32 v1, 6, v166
	v_and_b32_e32 v2, 15, v0
	v_lshrrev_b32_e32 v3, 4, v0
	v_lshlrev_b32_e32 v70, 4, v0
	v_add_u32_e32 v71, 0x1000, v70
	v_lshlrev_b32_e32 v248, 12, v2
	v_lshl_add_u32 v248, v1, 9, v248
	v_lshl_add_u32 v248, v3, 4, v248
	v_add_u32_e32 v249, 0x10000, v248
	v_add_u32_e32 v250, 0x20000, v248
	v_mul_u32_u24_e32 v251, 0xc00, v1
	v_mul_u32_u24_e32 v3, 0x300, v3
	v_add3_u32 v251, v251, v3, s29
	v_lshl_add_u32 v251, v2, 2, v251
	v_lshlrev_b32_e32 v49, 2, v166
	v_add_u32_e32 v47, s29, v49
	v_readfirstlane_b32 s46, v69
	s_lshl_b32 s45, s28, 4
	s_add_u32 s45, s45, s46
	s_sub_u32 s46, s45, 0x2000
	s_cmpk_ge_u32 s45, 0x2000
	s_cselect_b32 s98, s90, s92
	s_cselect_b32 s99, s91, s93
	s_cselect_b32 s46, s46, s45
	s_lshl_b32 s46, s46, 13
	s_add_u32 s98, s98, s46
	s_addc_u32 s99, s99, 0
	s_add_u32 s100, s98, 0x2000
	s_addc_u32 s101, s99, 0
	global_load_dwordx4 v[112:115], v70, s[98:99] offset:0 nt
	global_load_dwordx4 v[116:119], v70, s[98:99] offset:1024 nt
	global_load_dwordx4 v[120:123], v70, s[98:99] offset:2048 nt
	global_load_dwordx4 v[124:127], v70, s[98:99] offset:3072 nt
	global_load_dwordx4 v[128:131], v71, s[98:99] offset:0 nt
	global_load_dwordx4 v[132:135], v71, s[98:99] offset:1024 nt
	global_load_dwordx4 v[136:139], v71, s[98:99] offset:2048 nt
	global_load_dwordx4 v[140:143], v71, s[98:99] offset:3072 nt
	global_load_dwordx4 v[144:147], v70, s[100:101] offset:0 nt
	global_load_dwordx4 v[148:151], v70, s[100:101] offset:1024 nt
	global_load_dwordx4 v[152:155], v70, s[100:101] offset:2048 nt
	global_load_dwordx4 v[156:159], v70, s[100:101] offset:3072 nt
	global_load_dwordx4 v[160:163], v71, s[100:101] offset:0 nt
	global_load_dwordx4 v[232:235], v71, s[100:101] offset:1024 nt
	global_load_dwordx4 v[236:239], v71, s[100:101] offset:2048 nt
	global_load_dwordx4 v[240:243], v71, s[100:101] offset:3072 nt
	s_branch .LBB0_97

; DI f32x4 mfma16(bf16x8 a, bf16x8 b, f32x4 c) { return __builtin_amdgcn_mfma_f32_16x16x32_bf16(a, b, c, 0, 0, 0); }
; DI int otid() { int t = threadIdx.x; asm volatile("" : "+v"(t)); return t; }
; DI void skinny_tile(const P& p, int l, int r0, float* red) {
;     ...
;     const int tid = otid(), w = tid >> 6, lane = tid & 63, l15 = lane & 15, g = lane >> 4;
;     f32x4 acc[3];
; #pragma unroll
;     for (int n = 0; n < 3; ++n) acc[n] = (f32x4){0.f, 0.f, 0.f, 0.f};
;     const bf16_t* ap = A + (size_t)(r0 + l15) * DM + 256 * w + 8 * g;
;     const bf16_t* bp = Bt + (size_t)l15 * DM + 256 * w + 8 * g;
; #pragma unroll
;     for (int ks = 0; ks < 8; ++ks) {
;         const bf16x8 a0 = *(const bf16x8*)(ap + 32 * ks);
; #pragma unroll
;         for (int n = 0; n < 3; ++n) acc[n] = mfma16(a0, *(const bf16x8*)(bp + (size_t)16 * n * DM + 32 * ks), acc[n]);
;     }
.LBB0_103:
	s_waitcnt vmcnt(0)
	s_barrier
	s_lshl_b32 s20, s24, 12
	s_add_u32 s20, s10, s20
	s_addc_u32 s21, s11, 0
	global_load_dwordx4 v[0:3], v248, s[20:21] offset:0
	global_load_dwordx4 v[80:83], v248, s[12:13] offset:0
	global_load_dwordx4 v[84:87], v249, s[12:13] offset:0
	global_load_dwordx4 v[88:91], v250, s[12:13] offset:0
	global_load_dwordx4 v[4:7], v248, s[20:21] offset:64
	global_load_dwordx4 v[92:95], v248, s[12:13] offset:64
	global_load_dwordx4 v[96:99], v249, s[12:13] offset:64
	global_load_dwordx4 v[100:103], v250, s[12:13] offset:64
	global_load_dwordx4 v[8:11], v248, s[20:21] offset:128
	global_load_dwordx4 v[104:107], v248, s[12:13] offset:128
	global_load_dwordx4 v[108:111], v249, s[12:13] offset:128
	global_load_dwordx4 v[168:171], v250, s[12:13] offset:128
	global_load_dwordx4 v[12:15], v248, s[20:21] offset:192
	global_load_dwordx4 v[172:175], v248, s[12:13] offset:192
	global_load_dwordx4 v[176:179], v249, s[12:13] offset:192
	global_load_dwordx4 v[180:183], v250, s[12:13] offset:192
	global_load_dwordx4 v[16:19], v248, s[20:21] offset:256
	global_load_dwordx4 v[184:187], v248, s[12:13] offset:256
	global_load_dwordx4 v[188:191], v249, s[12:13] offset:256
	global_load_dwordx4 v[192:195], v250, s[12:13] offset:256
	global_load_dwordx4 v[20:23], v248, s[20:21] offset:320
	global_load_dwordx4 v[196:199], v248, s[12:13] offset:320
	global_load_dwordx4 v[200:203], v249, s[12:13] offset:320
	global_load_dwordx4 v[204:207], v250, s[12:13] offset:320
	global_load_dwordx4 v[24:27], v248, s[20:21] offset:384
	global_load_dwordx4 v[208:211], v248, s[12:13] offset:384
	global_load_dwordx4 v[212:215], v249, s[12:13] offset:384
	global_load_dwordx4 v[216:219], v250, s[12:13] offset:384
	global_load_dwordx4 v[28:31], v248, s[20:21] offset:448
	global_load_dwordx4 v[220:223], v248, s[12:13] offset:448
	global_load_dwordx4 v[224:227], v249, s[12:13] offset:448
	global_load_dwordx4 v[228:231], v250, s[12:13] offset:448
	s_add_i32 s47, s28, s70
	s_cmpk_gt_i32 s47, 0x23f
	s_cbranch_scc1 .Ln0_nopf
	v_readfirstlane_b32 s46, v69
	s_lshl_b32 s45, s47, 4
	s_add_u32 s45, s45, s46
	s_sub_u32 s46, s45, 0x2000
	s_cmpk_ge_u32 s45, 0x2000
	s_cselect_b32 s98, s90, s92
	s_cselect_b32 s99, s91, s93
	s_cselect_b32 s46, s46, s45
	s_lshl_b32 s46, s46, 13
	s_add_u32 s98, s98, s46
	s_addc_u32 s99, s99, 0
	s_add_u32 s100, s98, 0x2000
	s_addc_u32 s101, s99, 0
	global_load_dwordx4 v[112:115], v70, s[98:99] offset:0 nt
	global_load_dwordx4 v[116:119], v70, s[98:99] offset:1024 nt
	global_load_dwordx4 v[120:123], v70, s[98:99] offset:2048 nt
	global_load_dwordx4 v[124:127], v70, s[98:99] offset:3072 nt
	global_load_dwordx4 v[128:131], v71, s[98:99] offset:0 nt
	global_load_dwordx4 v[132:135], v71, s[98:99] offset:1024 nt
	global_load_dwordx4 v[136:139], v71, s[98:99] offset:2048 nt
	global_load_dwordx4 v[140:143], v71, s[98:99] offset:3072 nt
	global_load_dwordx4 v[144:147], v70, s[100:101] offset:0 nt
	global_load_dwordx4 v[148:151], v70, s[100:101] offset:1024 nt
	global_load_dwordx4 v[152:155], v70, s[100:101] offset:2048 nt
	global_load_dwordx4 v[156:159], v70, s[100:101] offset:3072 nt
	global_load_dwordx4 v[160:163], v71, s[100:101] offset:0 nt
	global_load_dwordx4 v[232:235], v71, s[100:101] offset:1024 nt
	global_load_dwordx4 v[236:239], v71, s[100:101] offset:2048 nt
	global_load_dwordx4 v[240:243], v71, s[100:101] offset:3072 nt
	s_waitcnt vmcnt(46)
	v_mfma_f32_16x16x32_bf16 v[60:63], v[0:3], v[80:83], 0
	s_waitcnt vmcnt(45)
	v_mfma_f32_16x16x32_bf16 v[64:67], v[0:3], v[84:87], 0
	s_waitcnt vmcnt(44)
	v_mfma_f32_16x16x32_bf16 v[244:247], v[0:3], v[88:91], 0
	s_waitcnt vmcnt(42)
	v_mfma_f32_16x16x32_bf16 v[60:63], v[4:7], v[92:95], v[60:63]
	s_waitcnt vmcnt(41)
	v_mfma_f32_16x16x32_bf16 v[64:67], v[4:7], v[96:99], v[64:67]
	s_waitcnt vmcnt(40)
	v_mfma_f32_16x16x32_bf16 v[244:247], v[4:7], v[100:103], v[244:247]
	s_waitcnt vmcnt(38)
	v_mfma_f32_16x16x32_bf16 v[60:63], v[8:11], v[104:107], v[60:63]
	s_waitcnt vmcnt(37)
	v_mfma_f32_16x16x32_bf16 v[64:67], v[8:11], v[108:111], v[64:67]
	s_waitcnt vmcnt(36)
	v_mfma_f32_16x16x32_bf16 v[244:247], v[8:11], v[168:171], v[244:247]
	s_waitcnt vmcnt(34)
	v_mfma_f32_16x16x32_bf16 v[60:63], v[12:15], v[172:175], v[60:63]
	s_waitcnt vmcnt(33)
	v_mfma_f32_16x16x32_bf16 v[64:67], v[12:15], v[176:179], v[64:67]
	s_waitcnt vmcnt(32)
	v_mfma_f32_16x16x32_bf16 v[244:247], v[12:15], v[180:183], v[244:247]
	s_waitcnt vmcnt(30)
	v_mfma_f32_16x16x32_bf16 v[60:63], v[16:19], v[184:187], v[60:63]
	s_waitcnt vmcnt(29)
	v_mfma_f32_16x16x32_bf16 v[64:67], v[16:19], v[188:191], v[64:67]
	s_waitcnt vmcnt(28)
	v_mfma_f32_16x16x32_bf16 v[244:247], v[16:19], v[192:195], v[244:247]
	s_waitcnt vmcnt(26)
	v_mfma_f32_16x16x32_bf16 v[60:63], v[20:23], v[196:199], v[60:63]
	s_waitcnt vmcnt(25)
	v_mfma_f32_16x16x32_bf16 v[64:67], v[20:23], v[200:203], v[64:67]
	s_waitcnt vmcnt(24)
	v_mfma_f32_16x16x32_bf16 v[244:247], v[20:23], v[204:207], v[244:247]
	s_waitcnt vmcnt(22)
	v_mfma_f32_16x16x32_bf16 v[60:63], v[24:27], v[208:211], v[60:63]
	s_waitcnt vmcnt(21)
	v_mfma_f32_16x16x32_bf16 v[64:67], v[24:27], v[212:215], v[64:67]
	s_waitcnt vmcnt(20)
	v_mfma_f32_16x16x32_bf16 v[244:247], v[24:27], v[216:219], v[244:247]
	s_waitcnt vmcnt(18)
	v_mfma_f32_16x16x32_bf16 v[60:63], v[28:31], v[220:223], v[60:63]
	s_waitcnt vmcnt(17)
	v_mfma_f32_16x16x32_bf16 v[64:67], v[28:31], v[224:227], v[64:67]
	s_waitcnt vmcnt(16)
	v_mfma_f32_16x16x32_bf16 v[244:247], v[28:31], v[228:231], v[244:247]
	s_branch .Ln0_join
; DI void skinny_tile(const P& p, int l, int r0, float* red) {
;     ...
; #pragma unroll
;     for (int n = 0; n < 3; ++n)
; #pragma unroll
;         for (int r = 0; r < 4; ++r) red[w * 768 + (4 * g + r) * 48 + 16 * n + l15] = acc[n][r];
;     __syncthreads();
;     for (int e = tid; e < 768; e += 512) {
;         float sum = 0.f;
; #pragma unroll
;         for (int k = 0; k < 8; ++k) sum += red[k * 768 + e];
;         G[(size_t)r0 * NNAR + e] = sum;
;     }
.Ln0_nopf:
	s_waitcnt vmcnt(30)
	v_mfma_f32_16x16x32_bf16 v[60:63], v[0:3], v[80:83], 0
	s_waitcnt vmcnt(29)
	v_mfma_f32_16x16x32_bf16 v[64:67], v[0:3], v[84:87], 0
	s_waitcnt vmcnt(28)
	v_mfma_f32_16x16x32_bf16 v[244:247], v[0:3], v[88:91], 0
	s_waitcnt vmcnt(26)
	v_mfma_f32_16x16x32_bf16 v[60:63], v[4:7], v[92:95], v[60:63]
	s_waitcnt vmcnt(25)
	v_mfma_f32_16x16x32_bf16 v[64:67], v[4:7], v[96:99], v[64:67]
	s_waitcnt vmcnt(24)
	v_mfma_f32_16x16x32_bf16 v[244:247], v[4:7], v[100:103], v[244:247]
	s_waitcnt vmcnt(22)
	v_mfma_f32_16x16x32_bf16 v[60:63], v[8:11], v[104:107], v[60:63]
	s_waitcnt vmcnt(21)
	v_mfma_f32_16x16x32_bf16 v[64:67], v[8:11], v[108:111], v[64:67]
	s_waitcnt vmcnt(20)
	v_mfma_f32_16x16x32_bf16 v[244:247], v[8:11], v[168:171], v[244:247]
	s_waitcnt vmcnt(18)
	v_mfma_f32_16x16x32_bf16 v[60:63], v[12:15], v[172:175], v[60:63]
	s_waitcnt vmcnt(17)
	v_mfma_f32_16x16x32_bf16 v[64:67], v[12:15], v[176:179], v[64:67]
	s_waitcnt vmcnt(16)
	v_mfma_f32_16x16x32_bf16 v[244:247], v[12:15], v[180:183], v[244:247]
	s_waitcnt vmcnt(14)
	v_mfma_f32_16x16x32_bf16 v[60:63], v[16:19], v[184:187], v[60:63]
	s_waitcnt vmcnt(13)
	v_mfma_f32_16x16x32_bf16 v[64:67], v[16:19], v[188:191], v[64:67]
	s_waitcnt vmcnt(12)
	v_mfma_f32_16x16x32_bf16 v[244:247], v[16:19], v[192:195], v[244:247]
	s_waitcnt vmcnt(10)
	v_mfma_f32_16x16x32_bf16 v[60:63], v[20:23], v[196:199], v[60:63]
	s_waitcnt vmcnt(9)
	v_mfma_f32_16x16x32_bf16 v[64:67], v[20:23], v[200:203], v[64:67]
	s_waitcnt vmcnt(8)
	v_mfma_f32_16x16x32_bf16 v[244:247], v[20:23], v[204:207], v[244:247]
	s_waitcnt vmcnt(6)
	v_mfma_f32_16x16x32_bf16 v[60:63], v[24:27], v[208:211], v[60:63]
	s_waitcnt vmcnt(5)
	v_mfma_f32_16x16x32_bf16 v[64:67], v[24:27], v[212:215], v[64:67]
	s_waitcnt vmcnt(4)
	v_mfma_f32_16x16x32_bf16 v[244:247], v[24:27], v[216:219], v[244:247]
	s_waitcnt vmcnt(2)
	v_mfma_f32_16x16x32_bf16 v[60:63], v[28:31], v[220:223], v[60:63]
	s_waitcnt vmcnt(1)
	v_mfma_f32_16x16x32_bf16 v[64:67], v[28:31], v[224:227], v[64:67]
	s_waitcnt vmcnt(0)
	v_mfma_f32_16x16x32_bf16 v[244:247], v[28:31], v[228:231], v[244:247]
.Ln0_join:
	s_nop 9
	ds_write_b32 v251, v60 offset:0
	ds_write_b32 v251, v61 offset:192
	ds_write_b32 v251, v62 offset:384
	ds_write_b32 v251, v63 offset:576
	ds_write_b32 v251, v64 offset:64
	ds_write_b32 v251, v65 offset:256
	ds_write_b32 v251, v66 offset:448
	ds_write_b32 v251, v67 offset:640
	ds_write_b32 v251, v244 offset:128
	ds_write_b32 v251, v245 offset:320
	ds_write_b32 v251, v246 offset:512
	ds_write_b32 v251, v247 offset:704
	s_waitcnt lgkmcnt(0)
	s_barrier
	ds_read_b32 v0, v47 offset:0
	ds_read_b32 v1, v47 offset:3072
	ds_read_b32 v2, v47 offset:6144
	ds_read_b32 v3, v47 offset:9216
	ds_read_b32 v4, v47 offset:12288
	ds_read_b32 v5, v47 offset:15360
	ds_read_b32 v6, v47 offset:18432
	ds_read_b32 v7, v47 offset:21504
	ds_read_b32 v8, v47 offset:2048
	ds_read_b32 v9, v47 offset:5120
	ds_read_b32 v10, v47 offset:8192
	ds_read_b32 v11, v47 offset:11264
	ds_read_b32 v12, v47 offset:14336
	ds_read_b32 v13, v47 offset:17408
	ds_read_b32 v14, v47 offset:20480
	ds_read_b32 v15, v47 offset:23552
	s_mul_i32 s20, s24, 0xc0
	s_add_u32 s20, s31, s20
	s_addc_u32 s21, s34, 0
	s_waitcnt lgkmcnt(8)
	v_add_f32_e32 v16, 0, v0
	v_add_f32_e32 v16, v16, v1
	v_add_f32_e32 v16, v16, v2
	v_add_f32_e32 v16, v16, v3
	v_add_f32_e32 v16, v16, v4
	v_add_f32_e32 v16, v16, v5
	v_add_f32_e32 v16, v16, v6
	v_add_f32_e32 v16, v16, v7
	s_waitcnt lgkmcnt(0)
	v_add_f32_e32 v17, 0, v8
	v_add_f32_e32 v17, v17, v9
	v_add_f32_e32 v17, v17, v10
	v_add_f32_e32 v17, v17, v11
	v_add_f32_e32 v17, v17, v12
	v_add_f32_e32 v17, v17, v13
	v_add_f32_e32 v17, v17, v14
	v_add_f32_e32 v17, v17, v15
	global_store_dword v49, v16, s[20:21]
	v_cmp_gt_u32_e32 vcc, 0x100, v166
	s_and_saveexec_b64 s[22:23], vcc
	global_store_dword v49, v17, s[20:21] offset:2048
	s_mov_b64 exec, s[22:23]
	s_branch .LBB0_96
